# 16-lane sum/max reductions in attention and pass3 (hgrn/retention) via DPP quad_perm/row_mirror instead of ds_bpermute round trips
# speedup vs baseline: 1.0075x; 1.0075x over previous
; #define LAS __attribute__((address_space(3)))
; __device__ __forceinline__ unsigned cvt_pk_bf16(float lo, float hi) { unsigned r; asm("v_cvt_pk_bf16_f32 %0, %1, %2" : "=v"(r) : "v"(lo), "v"(hi)); return r; }
; __device__ __forceinline__ float lo_bf(unsigned u) { return __uint_as_float(u << 16); }
; __device__ __forceinline__ float hi_bf(unsigned u) { return __uint_as_float(u & 0xffff0000u); }
; __device__ __forceinline__ void attn_phase(const Params& p, int l, bf16_t* PROJ, LAS unsigned char* L) {
;     ...
;             __syncthreads();
; #pragma unroll
;             for (int i = 0; i < 4; ++i) { const int pi = tid + 512 * i, h2 = pi >> 10, rem = pi & 1023, key = rem >> 4, part = rem & 15;
;                 const u32x4 raw = kr[i]; float ss = 0.f;
; #pragma unroll
;                 for (int e = 0; e < 4; ++e) { const float a = lo_bf(raw[e]), b = hi_bf(raw[e]); ss += a * a + b * b; }
;                 ss += __shfl_xor(ss, 1); ss += __shfl_xor(ss, 2); ss += __shfl_xor(ss, 4); ss += __shfl_xor(ss, 8);
;                 const float rs = rsqrtf(ss * (1.0f / 128.0f) + EPS); u32x4 w;
; #pragma unroll
;                 for (int e = 0; e < 4; ++e) w[e] = cvt_pk_bf16(lo_bf(raw[e]) * rs, hi_bf(raw[e]) * rs);
;                 *(LAS u32x4*)(Ks + h2 * (64 * 136) + key * 136 + part * 8) = w; }
;             v_store(Vs, vr[0], tid); v_store(Vs + 16384, vr[1], tid);
.LBB0_348:
	s_waitcnt vmcnt(0)
	v_and_b32_e32 v83, 0xffff0000, v69
	v_and_b32_e32 v82, 0xffff0000, v68
	v_lshlrev_b32_e32 v81, 16, v69
	v_lshlrev_b32_e32 v80, 16, v68
	v_pk_mul_f32 v[84:85], v[82:83], v[82:83]
	v_and_b32_e32 v89, 0xffff0000, v71
	v_and_b32_e32 v88, 0xffff0000, v70
	v_pk_fma_f32 v[84:85], v[80:81], v[80:81], v[84:85]
	v_lshlrev_b32_e32 v87, 16, v71
	v_lshlrev_b32_e32 v86, 16, v70
	v_pk_mul_f32 v[90:91], v[88:89], v[88:89]
	v_add_f32_e32 v84, v84, v85
	v_pk_fma_f32 v[90:91], v[86:87], v[86:87], v[90:91]
	s_nop 0
	v_add_f32_e32 v84, v90, v84
	v_add_f32_e32 v84, v91, v84
	s_barrier
	s_waitcnt lgkmcnt(0)
	s_cmp_eq_u32 s3, 8
	s_nop 1
	v_add_f32_dpp v84, v84, v84 quad_perm:[1,0,3,2] row_mask:0xf bank_mask:0xf
	s_waitcnt lgkmcnt(0)
	s_nop 1
	v_add_f32_dpp v84, v84, v84 quad_perm:[2,3,0,1] row_mask:0xf bank_mask:0xf
	s_waitcnt lgkmcnt(0)
	s_nop 1
	v_add_f32_dpp v84, v84, v84 row_half_mirror row_mask:0xf bank_mask:0xf
	s_waitcnt lgkmcnt(0)
	s_nop 1
	v_add_f32_dpp v84, v84, v84 row_mirror row_mask:0xf bank_mask:0xf
	v_fmamk_f32 v84, v84, 0x3c000000, v164
	v_cmp_gt_f32_e32 vcc, s33, v84
	v_mul_f32_e32 v85, 0x4b800000, v84
	s_nop 0
	v_cndmask_b32_e32 v84, v84, v85, vcc
	v_rsq_f32_e32 v84, v84
	s_nop 0
	v_mul_f32_e32 v85, 0x45800000, v84
	v_cndmask_b32_e32 v84, v84, v85, vcc
	v_mul_f32_e32 v80, v84, v80
	v_mul_f32_e32 v82, v84, v82
	v_cvt_pk_bf16_f32 v80, v80, v82
	v_mul_f32_e32 v81, v84, v81
	v_mul_f32_e32 v82, v84, v83
	v_cvt_pk_bf16_f32 v81, v81, v82
	v_mul_f32_e32 v82, v84, v86
	v_mul_f32_e32 v83, v84, v88
	v_cvt_pk_bf16_f32 v82, v82, v83
	v_mul_f32_e32 v83, v84, v87
	v_mul_f32_e32 v84, v84, v89
	v_cvt_pk_bf16_f32 v83, v83, v84
	ds_write_b128 v187, v[80:83]
	v_and_b32_e32 v83, 0xffff0000, v65
	v_and_b32_e32 v82, 0xffff0000, v64
	v_lshlrev_b32_e32 v81, 16, v65
	v_lshlrev_b32_e32 v80, 16, v64
	v_pk_mul_f32 v[84:85], v[82:83], v[82:83]
	v_and_b32_e32 v89, 0xffff0000, v67
	v_and_b32_e32 v88, 0xffff0000, v66
	v_pk_fma_f32 v[84:85], v[80:81], v[80:81], v[84:85]
	v_lshlrev_b32_e32 v87, 16, v67
	v_lshlrev_b32_e32 v86, 16, v66
	v_pk_mul_f32 v[90:91], v[88:89], v[88:89]
	v_add_f32_e32 v84, v84, v85
	v_pk_fma_f32 v[90:91], v[86:87], v[86:87], v[90:91]
	s_nop 0
	v_add_f32_e32 v84, v90, v84
	v_add_f32_e32 v84, v91, v84
	s_waitcnt lgkmcnt(0)
	s_nop 1
	v_add_f32_dpp v84, v84, v84 quad_perm:[1,0,3,2] row_mask:0xf bank_mask:0xf
	s_waitcnt lgkmcnt(0)
	s_nop 1
	v_add_f32_dpp v84, v84, v84 quad_perm:[2,3,0,1] row_mask:0xf bank_mask:0xf
	s_waitcnt lgkmcnt(0)
	s_nop 1
	v_add_f32_dpp v84, v84, v84 row_half_mirror row_mask:0xf bank_mask:0xf
	s_waitcnt lgkmcnt(0)
	s_nop 1
	v_add_f32_dpp v84, v84, v84 row_mirror row_mask:0xf bank_mask:0xf
	v_fmamk_f32 v84, v84, 0x3c000000, v164
	v_cmp_gt_f32_e32 vcc, s33, v84
	v_mul_f32_e32 v85, 0x4b800000, v84
	s_nop 0
	v_cndmask_b32_e32 v84, v84, v85, vcc
	v_rsq_f32_e32 v84, v84
	s_nop 0
	v_mul_f32_e32 v85, 0x45800000, v84
	v_cndmask_b32_e32 v84, v84, v85, vcc
	v_mul_f32_e32 v80, v84, v80
	v_mul_f32_e32 v82, v84, v82
	v_cvt_pk_bf16_f32 v80, v80, v82
	v_mul_f32_e32 v81, v84, v81
	v_mul_f32_e32 v82, v84, v83
	v_cvt_pk_bf16_f32 v81, v81, v82
	v_mul_f32_e32 v82, v84, v86
	v_mul_f32_e32 v83, v84, v88
	v_cvt_pk_bf16_f32 v82, v82, v83
	v_mul_f32_e32 v83, v84, v87
	v_mul_f32_e32 v84, v84, v89
	v_cvt_pk_bf16_f32 v83, v83, v84
	ds_write_b128 v188, v[80:83]
	v_and_b32_e32 v83, 0xffff0000, v61
	v_and_b32_e32 v82, 0xffff0000, v60
	v_lshlrev_b32_e32 v81, 16, v61
	v_lshlrev_b32_e32 v80, 16, v60
	v_pk_mul_f32 v[84:85], v[82:83], v[82:83]
	v_and_b32_e32 v89, 0xffff0000, v63
	v_and_b32_e32 v88, 0xffff0000, v62
	v_pk_fma_f32 v[84:85], v[80:81], v[80:81], v[84:85]
	v_lshlrev_b32_e32 v87, 16, v63
	v_lshlrev_b32_e32 v86, 16, v62
	v_pk_mul_f32 v[90:91], v[88:89], v[88:89]
	v_add_f32_e32 v84, v84, v85
	v_pk_fma_f32 v[90:91], v[86:87], v[86:87], v[90:91]
	s_nop 0
	v_add_f32_e32 v84, v90, v84
	v_add_f32_e32 v84, v91, v84
	s_waitcnt lgkmcnt(0)
	s_nop 1
	v_add_f32_dpp v84, v84, v84 quad_perm:[1,0,3,2] row_mask:0xf bank_mask:0xf
	s_waitcnt lgkmcnt(0)
	s_nop 1
	v_add_f32_dpp v84, v84, v84 quad_perm:[2,3,0,1] row_mask:0xf bank_mask:0xf
	s_waitcnt lgkmcnt(0)
	s_nop 1
	v_add_f32_dpp v84, v84, v84 row_half_mirror row_mask:0xf bank_mask:0xf
	s_waitcnt lgkmcnt(0)
	s_nop 1
	v_add_f32_dpp v84, v84, v84 row_mirror row_mask:0xf bank_mask:0xf
	v_fmamk_f32 v84, v84, 0x3c000000, v164
	v_cmp_gt_f32_e32 vcc, s33, v84
	v_mul_f32_e32 v85, 0x4b800000, v84
	s_nop 0
	v_cndmask_b32_e32 v84, v84, v85, vcc
	v_rsq_f32_e32 v84, v84
	s_nop 0
	v_mul_f32_e32 v85, 0x45800000, v84
	v_cndmask_b32_e32 v84, v84, v85, vcc
	v_mul_f32_e32 v80, v84, v80
	v_mul_f32_e32 v82, v84, v82
	v_cvt_pk_bf16_f32 v80, v80, v82
	v_mul_f32_e32 v81, v84, v81
	v_mul_f32_e32 v82, v84, v83
	v_cvt_pk_bf16_f32 v81, v81, v82
	v_mul_f32_e32 v82, v84, v86
	v_mul_f32_e32 v83, v84, v88
	v_cvt_pk_bf16_f32 v82, v82, v83
	v_mul_f32_e32 v83, v84, v87
	v_mul_f32_e32 v84, v84, v89
	v_cvt_pk_bf16_f32 v83, v83, v84
	ds_write_b128 v189, v[80:83]
	v_and_b32_e32 v83, 0xffff0000, v57
	v_and_b32_e32 v82, 0xffff0000, v56
	v_lshlrev_b32_e32 v81, 16, v57
	v_lshlrev_b32_e32 v80, 16, v56
	v_pk_mul_f32 v[84:85], v[82:83], v[82:83]
	v_and_b32_e32 v89, 0xffff0000, v59
	v_and_b32_e32 v88, 0xffff0000, v58
	v_pk_fma_f32 v[84:85], v[80:81], v[80:81], v[84:85]
	v_lshlrev_b32_e32 v87, 16, v59
	v_lshlrev_b32_e32 v86, 16, v58
	v_pk_mul_f32 v[90:91], v[88:89], v[88:89]
	v_add_f32_e32 v84, v84, v85
	v_pk_fma_f32 v[90:91], v[86:87], v[86:87], v[90:91]
	s_nop 0
	v_add_f32_e32 v84, v90, v84
	v_add_f32_e32 v84, v91, v84
	s_waitcnt lgkmcnt(0)
	s_nop 1
	v_add_f32_dpp v84, v84, v84 quad_perm:[1,0,3,2] row_mask:0xf bank_mask:0xf
	s_waitcnt lgkmcnt(0)
	s_nop 1
	v_add_f32_dpp v84, v84, v84 quad_perm:[2,3,0,1] row_mask:0xf bank_mask:0xf
	s_waitcnt lgkmcnt(0)
	s_nop 1
	v_add_f32_dpp v84, v84, v84 row_half_mirror row_mask:0xf bank_mask:0xf
	s_waitcnt lgkmcnt(0)
	s_nop 1
	v_add_f32_dpp v84, v84, v84 row_mirror row_mask:0xf bank_mask:0xf
	v_fmamk_f32 v84, v84, 0x3c000000, v164
	v_cmp_gt_f32_e32 vcc, s33, v84
	v_mul_f32_e32 v85, 0x4b800000, v84
	s_nop 0
	v_cndmask_b32_e32 v84, v84, v85, vcc
	v_rsq_f32_e32 v84, v84
	s_nop 0
	v_mul_f32_e32 v85, 0x45800000, v84
	v_cndmask_b32_e32 v84, v84, v85, vcc
	v_mul_f32_e32 v80, v84, v80
	v_mul_f32_e32 v82, v84, v82
	v_cvt_pk_bf16_f32 v80, v80, v82
	v_mul_f32_e32 v81, v84, v81
	v_mul_f32_e32 v82, v84, v83
	v_cvt_pk_bf16_f32 v81, v81, v82
	v_mul_f32_e32 v82, v84, v86
	v_mul_f32_e32 v83, v84, v88
	v_cvt_pk_bf16_f32 v82, v82, v83
	v_mul_f32_e32 v83, v84, v87
	v_mul_f32_e32 v84, v84, v89
	v_cvt_pk_bf16_f32 v83, v83, v84
	ds_write_b128 v190, v[80:83]
	ds_write_b128 v196, v[48:51] offset:34816
	ds_write_b128 v197, v[52:55] offset:34816
	ds_write_b128 v196, v[72:75] offset:51200
	ds_write_b128 v197, v[76:79] offset:51200
	s_cbranch_scc1 .LBB0_350
; __device__ __forceinline__ void attn_phase(const Params& p, int l, bf16_t* PROJ, LAS unsigned char* L) {
;     ...
;             if (j < 8) ATT_LOAD(n - 8 + j + 1);
	v_add_u32_e32 v50, s22, v181
	v_mov_b64_e32 v[48:49], s[14:15]
	v_mad_i64_i32 v[48:49], s[20:21], v50, s62, v[48:49]
	v_lshl_add_u64 v[50:51], v[120:121], 1, v[48:49]
	v_lshl_add_u64 v[50:51], v[50:51], 0, v[136:137]
	v_add_u32_e32 v52, s22, v183
	v_mad_i64_i32 v[52:53], s[20:21], v52, s62, v[124:125]
	global_load_dwordx4 v[68:71], v[50:51], off offset:2048
	global_load_dwordx4 v[64:67], v[52:53], off offset:2048
	v_add_u32_e32 v50, s22, v186
	v_mad_i64_i32 v[50:51], s[20:21], v50, s62, v[126:127]
	s_mul_i32 s21, s22, 0x5000
	s_mul_hi_i32 s20, s22, 0x5000
	s_add_u32 s21, s14, s21
	s_addc_u32 s34, s15, s20
	s_add_u32 s20, s21, 0x1000
	s_addc_u32 s21, s34, 0
	v_lshl_add_u64 v[48:49], v[122:123], 1, v[48:49]
	s_add_u32 s34, s20, s23
	v_lshl_add_u64 v[48:49], v[48:49], 0, v[136:137]
	s_addc_u32 s35, s21, 0
	v_lshl_add_u64 v[72:73], s[20:21], 0, v[136:137]
	global_load_dwordx4 v[60:63], v[48:49], off offset:2048
	global_load_dwordx4 v[56:59], v[50:51], off offset:2048
	v_lshl_add_u64 v[48:49], s[34:35], 0, v[136:137]
	v_lshl_add_u64 v[74:75], v[72:73], 0, v[104:105]
	v_lshl_add_u64 v[72:73], v[72:73], 0, v[106:107]
	v_lshl_add_u64 v[50:51], v[48:49], 0, v[104:105]
	v_lshl_add_u64 v[52:53], v[48:49], 0, v[106:107]
	v_lshl_add_u64 v[74:75], v[74:75], 0, s[36:37]
	v_lshl_add_u64 v[76:77], v[72:73], 0, s[36:37]
	global_load_dwordx4 v[48:51], v[50:51], off
	s_nop 0
	global_load_dwordx4 v[52:55], v[52:53], off
	s_nop 0
	global_load_dwordx4 v[72:75], v[74:75], off
	s_nop 0
	global_load_dwordx4 v[76:79], v[76:77], off

; #define LAS __attribute__((address_space(3)))
; __device__ __forceinline__ bf16_t f2bf(float f) { return (bf16_t)((__float_as_uint(f) + 0x8000u) >> 16); }
; __device__ __forceinline__ void attn_phase(const Params& p, int l, bf16_t* PROJ, LAS unsigned char* L) {
;     ...
; #pragma unroll
;             for (int jj = 0; jj < 4; ++jj) {
;                 float tm = fmaxf(fmaxf(s[0][jj], s[1][jj]), fmaxf(s[2][jj], s[3][jj]));
;                 tm = fmaxf(tm, __shfl_xor(tm, 1)); tm = fmaxf(tm, __shfl_xor(tm, 2)); tm = fmaxf(tm, __shfl_xor(tm, 4)); tm = fmaxf(tm, __shfl_xor(tm, 8));
;                 const float mn = fmaxf(mrow[jj], tm), alpha = __builtin_amdgcn_exp2f(mrow[jj] - mn); mrow[jj] = mn;
;                 float rsum = 0.f;
; #pragma unroll
;                 for (int nt = 0; nt < 4; ++nt) { const float pv = __builtin_amdgcn_exp2f(s[nt][jj] - mn); s[nt][jj] = pv; rsum += pv; }
;                 lsum[jj] = lsum[jj] * alpha + rsum;
; #pragma unroll
;                 for (int e = 0; e < 8; ++e) O[e][jj] *= alpha;
;             }
;             LAS bf16_t* Pw = Ps + wid * (16 * 72);
; #pragma unroll
;             for (int nt = 0; nt < 4; ++nt)
; #pragma unroll
;                 for (int jj = 0; jj < 4; ++jj) Pw[(fq * 4 + jj) * 72 + nt * 16 + fr] = f2bf(s[nt][jj]);
.LBB0_354:
	v_max_f32_e32 v80, v148, v148
	v_max_f32_e32 v81, v146, v146
	v_max_f32_e32 v80, v81, v80
	v_max3_f32 v80, v142, v144, v80
	v_max_f32_e32 v82, v147, v147
	v_max_f32_e32 v92, v131, v131
	s_add_i32 s20, s3, 1
	s_add_i32 s22, s22, 64
	s_waitcnt lgkmcnt(0)
	s_nop 1
	v_max_f32_dpp v80, v80, v80 quad_perm:[1,0,3,2] row_mask:0xf bank_mask:0xf
	v_subrev_u32_e32 v113, 64, v113
	s_cmp_gt_i32 s3, 7
	s_waitcnt lgkmcnt(0)
	s_nop 1
	v_max_f32_dpp v80, v80, v80 quad_perm:[2,3,0,1] row_mask:0xf bank_mask:0xf
	s_waitcnt lgkmcnt(0)
	s_nop 1
	v_max_f32_dpp v80, v80, v80 row_half_mirror row_mask:0xf bank_mask:0xf
	s_nop 1
	v_mov_b32_dpp v81, v80 row_mirror row_mask:0xf bank_mask:0xf
	s_waitcnt lgkmcnt(0)
	v_max3_f32 v221, v220, v80, v81
	v_sub_f32_e32 v80, v220, v221
	v_exp_f32_e32 v89, v80
	v_max_f32_e32 v80, v149, v149
	v_max_f32_e32 v80, v82, v80
	v_max3_f32 v80, v143, v145, v80
	v_sub_f32_e32 v81, v142, v221
	v_exp_f32_e32 v87, v81
	v_sub_f32_e32 v81, v144, v221
	v_exp_f32_e32 v85, v81
	s_waitcnt lgkmcnt(0)
	s_nop 1
	v_max_f32_dpp v80, v80, v80 quad_perm:[1,0,3,2] row_mask:0xf bank_mask:0xf
	v_sub_f32_e32 v81, v146, v221
	v_exp_f32_e32 v83, v81
	v_sub_f32_e32 v81, v148, v221
	v_exp_f32_e32 v81, v81
	s_waitcnt lgkmcnt(0)
	s_nop 1
	v_max_f32_dpp v80, v80, v80 quad_perm:[2,3,0,1] row_mask:0xf bank_mask:0xf
	s_waitcnt lgkmcnt(0)
	s_nop 1
	v_max_f32_dpp v80, v80, v80 row_half_mirror row_mask:0xf bank_mask:0xf
	s_nop 1
	v_mov_b32_dpp v82, v80 row_mirror row_mask:0xf bank_mask:0xf
	s_waitcnt lgkmcnt(0)
	v_max3_f32 v144, v219, v80, v82
	v_sub_f32_e32 v80, v143, v144
	v_exp_f32_e32 v86, v80
	v_sub_f32_e32 v80, v145, v144
	v_exp_f32_e32 v84, v80
	v_sub_f32_e32 v80, v147, v144
	v_exp_f32_e32 v82, v80
	v_sub_f32_e32 v80, v149, v144
	v_sub_f32_e32 v88, v219, v144
	v_exp_f32_e32 v80, v80
	v_exp_f32_e32 v88, v88
	v_pk_add_f32 v[90:91], v[86:87], 0 op_sel_hi:[1,0]
	v_add_u32_e32 v86, 0x8000, v86
	v_pk_add_f32 v[90:91], v[84:85], v[90:91]
	v_add_u32_e32 v84, 0x8000, v84
	v_pk_add_f32 v[90:91], v[82:83], v[90:91]
	v_add_u32_e32 v82, 0x8000, v82
	v_pk_add_f32 v[90:91], v[80:81], v[90:91]
	v_add_u32_e32 v80, 0x8000, v80
	v_pk_fma_f32 v[118:119], v[118:119], v[88:89], v[90:91]
	v_max_f32_e32 v90, v128, v128
	v_max_f32_e32 v91, v130, v130
	v_max_f32_e32 v90, v91, v90
	v_max3_f32 v90, v134, v132, v90
	ds_write_b16_d16_hi v199, v86 offset:144
	ds_write_b16_d16_hi v199, v84 offset:176
	ds_write_b16_d16_hi v199, v82 offset:208
	ds_write_b16_d16_hi v199, v80 offset:240
	s_waitcnt lgkmcnt(4)
	s_nop 1
	v_max_f32_dpp v90, v90, v90 quad_perm:[1,0,3,2] row_mask:0xf bank_mask:0xf
	v_add_u32_e32 v87, 0x8000, v87
	v_add_u32_e32 v85, 0x8000, v85
	v_add_u32_e32 v83, 0x8000, v83
	v_add_u32_e32 v81, 0x8000, v81
	s_waitcnt lgkmcnt(0)
	s_nop 1
	v_max_f32_dpp v90, v90, v90 quad_perm:[2,3,0,1] row_mask:0xf bank_mask:0xf
	ds_write_b16_d16_hi v199, v87
	ds_write_b16_d16_hi v199, v85 offset:32
	ds_write_b16_d16_hi v199, v83 offset:64
	ds_write_b16_d16_hi v199, v81 offset:96
	s_waitcnt lgkmcnt(4)
	s_nop 1
	v_max_f32_dpp v90, v90, v90 row_half_mirror row_mask:0xf bank_mask:0xf
	s_nop 1
	v_mov_b32_dpp v91, v90 row_mirror row_mask:0xf bank_mask:0xf
	s_waitcnt lgkmcnt(0)
	v_max3_f32 v145, v218, v90, v91
	v_sub_f32_e32 v90, v218, v145
	v_exp_f32_e32 v147, v90
	v_max_f32_e32 v90, v129, v129
	v_max_f32_e32 v90, v92, v90
	v_max3_f32 v90, v135, v133, v90
	v_sub_f32_e32 v91, v134, v145
	v_exp_f32_e32 v143, v91
	v_sub_f32_e32 v91, v132, v145
	v_exp_f32_e32 v95, v91
	s_waitcnt lgkmcnt(0)
	s_nop 1
	v_max_f32_dpp v90, v90, v90 quad_perm:[1,0,3,2] row_mask:0xf bank_mask:0xf
	v_sub_f32_e32 v91, v130, v145
	v_exp_f32_e32 v93, v91
	v_sub_f32_e32 v91, v128, v145
	v_exp_f32_e32 v91, v91
	s_waitcnt lgkmcnt(0)
	s_nop 1
	v_max_f32_dpp v90, v90, v90 quad_perm:[2,3,0,1] row_mask:0xf bank_mask:0xf
	v_add_u32_e32 v86, 0x8000, v143
	v_add_u32_e32 v84, 0x8000, v95
	v_add_u32_e32 v82, 0x8000, v93
	v_add_u32_e32 v80, 0x8000, v91
	s_waitcnt lgkmcnt(0)
	s_nop 1
	v_max_f32_dpp v90, v90, v90 row_half_mirror row_mask:0xf bank_mask:0xf
	s_nop 1
	v_mov_b32_dpp v92, v90 row_mirror row_mask:0xf bank_mask:0xf
	ds_write_b16_d16_hi v199, v86 offset:288
	ds_write_b16_d16_hi v199, v84 offset:320
	ds_write_b16_d16_hi v199, v82 offset:352
	ds_write_b16_d16_hi v199, v80 offset:384
	s_waitcnt lgkmcnt(4)
; #define LAS __attribute__((address_space(3)))
; __device__ __forceinline__ bf16_t f2bf(float f) { return (bf16_t)((__float_as_uint(f) + 0x8000u) >> 16); }
; #define MFMA16(a, b, c) __builtin_amdgcn_mfma_f32_16x16x32_bf16(a, b, c, 0, 0, 0)
; __device__ __forceinline__ void attn_phase(const Params& p, int l, bf16_t* PROJ, LAS unsigned char* L) {
;     ...
;                 const float mn = fmaxf(mrow[jj], tm), alpha = __builtin_amdgcn_exp2f(mrow[jj] - mn); mrow[jj] = mn;
;                 float rsum = 0.f;
; #pragma unroll
;                 for (int nt = 0; nt < 4; ++nt) { const float pv = __builtin_amdgcn_exp2f(s[nt][jj] - mn); s[nt][jj] = pv; rsum += pv; }
;                 lsum[jj] = lsum[jj] * alpha + rsum;
; #pragma unroll
;                 for (int e = 0; e < 8; ++e) O[e][jj] *= alpha;
;             }
;             LAS bf16_t* Pw = Ps + wid * (16 * 72);
; #pragma unroll
;             for (int nt = 0; nt < 4; ++nt)
; #pragma unroll
;                 for (int jj = 0; jj < 4; ++jj) Pw[(fq * 4 + jj) * 72 + nt * 16 + fr] = f2bf(s[nt][jj]);
; #pragma unroll
;             for (int ks = 0; ks < 2; ++ks) { const bf16x8 a = LDFRAG(Pw, fr, 72, ks * 32 + fq * 8);
; #pragma unroll
;                 for (int e = 0; e < 8; ++e) O[e] = MFMA16(a, v_frag(Vs + hh * 16384, lane, e, ks), O[e]); }
	v_max3_f32 v128, v217, v90, v92
	v_sub_f32_e32 v90, v135, v128
	v_exp_f32_e32 v142, v90
	v_sub_f32_e32 v90, v133, v128
	v_exp_f32_e32 v94, v90
	v_sub_f32_e32 v90, v131, v128
	v_exp_f32_e32 v92, v90
	v_sub_f32_e32 v90, v129, v128
	v_exp_f32_e32 v90, v90
	v_sub_f32_e32 v130, v217, v128
	v_add_u32_e32 v86, 0x8000, v142
	v_add_u32_e32 v84, 0x8000, v94
	v_add_u32_e32 v82, 0x8000, v92
	v_add_u32_e32 v80, 0x8000, v90
	v_exp_f32_e32 v146, v130
	v_pk_add_f32 v[130:131], v[142:143], 0 op_sel_hi:[1,0]
	ds_write_b16_d16_hi v199, v86 offset:432
	ds_write_b16_d16_hi v199, v84 offset:464
	ds_write_b16_d16_hi v199, v82 offset:496
	ds_write_b16_d16_hi v199, v80 offset:528
	v_pk_add_f32 v[130:131], v[94:95], v[130:131]
	ds_read_b128 v[80:83], v160
	ds_read_b64_tr_b16 v[84:85], v200 offset:34816
	ds_read_b64_tr_b16 v[86:87], v201 offset:35840
	v_pk_add_f32 v[130:131], v[92:93], v[130:131]
	v_mov_b32_e32 v132, v89
	v_pk_add_f32 v[130:131], v[90:91], v[130:131]
	v_mov_b32_e32 v133, v88
	v_pk_fma_f32 v[116:117], v[116:117], v[146:147], v[130:131]
	v_mov_b32_e32 v130, v147
	v_mov_b32_e32 v131, v146
	v_pk_mul_f32 v[18:19], v[18:19], v[130:131]
	v_pk_mul_f32 v[16:17], v[16:17], v[132:133]
	v_pk_mul_f32 v[22:23], v[22:23], v[130:131]
	v_pk_mul_f32 v[20:21], v[20:21], v[132:133]
	s_waitcnt lgkmcnt(0)
	v_mfma_f32_16x16x32_bf16 v[16:19], v[80:83], v[84:87], v[16:19]
	ds_read_b64_tr_b16 v[84:85], v202 offset:34816
	ds_read_b64_tr_b16 v[86:87], v203 offset:35840
	v_pk_mul_f32 v[26:27], v[26:27], v[130:131]
	v_pk_mul_f32 v[24:25], v[24:25], v[132:133]
	s_waitcnt lgkmcnt(0)
	v_mfma_f32_16x16x32_bf16 v[20:23], v[80:83], v[84:87], v[20:23]
	ds_read_b64_tr_b16 v[84:85], v204 offset:34816
	ds_read_b64_tr_b16 v[86:87], v205 offset:35840
	v_pk_mul_f32 v[30:31], v[30:31], v[130:131]
	v_pk_mul_f32 v[28:29], v[28:29], v[132:133]
	s_waitcnt lgkmcnt(0)
	v_mfma_f32_16x16x32_bf16 v[24:27], v[80:83], v[84:87], v[24:27]
	ds_read_b64_tr_b16 v[84:85], v206 offset:34816
	ds_read_b64_tr_b16 v[86:87], v207 offset:35840
	v_pk_mul_f32 v[34:35], v[34:35], v[130:131]
	v_pk_mul_f32 v[32:33], v[32:33], v[132:133]
	s_waitcnt lgkmcnt(0)
	v_mfma_f32_16x16x32_bf16 v[28:31], v[80:83], v[84:87], v[28:31]
	ds_read_b64_tr_b16 v[84:85], v208 offset:34816
	ds_read_b64_tr_b16 v[86:87], v209 offset:35840
	v_pk_mul_f32 v[38:39], v[38:39], v[130:131]
	v_pk_mul_f32 v[36:37], v[36:37], v[132:133]
	s_waitcnt lgkmcnt(0)
	v_mfma_f32_16x16x32_bf16 v[32:35], v[80:83], v[84:87], v[32:35]
	ds_read_b64_tr_b16 v[84:85], v210 offset:34816
	ds_read_b64_tr_b16 v[86:87], v211 offset:35840
	v_pk_mul_f32 v[42:43], v[42:43], v[130:131]
	v_pk_mul_f32 v[40:41], v[40:41], v[132:133]
	s_waitcnt lgkmcnt(0)
	v_mfma_f32_16x16x32_bf16 v[36:39], v[80:83], v[84:87], v[36:39]
	ds_read_b64_tr_b16 v[84:85], v212 offset:34816
	ds_read_b64_tr_b16 v[86:87], v213 offset:35840
	v_pk_mul_f32 v[46:47], v[46:47], v[130:131]
	v_pk_mul_f32 v[44:45], v[44:45], v[132:133]
	s_waitcnt lgkmcnt(0)
	v_mfma_f32_16x16x32_bf16 v[40:43], v[80:83], v[84:87], v[40:43]
	ds_read_b64_tr_b16 v[84:85], v214 offset:34816
	ds_read_b64_tr_b16 v[86:87], v215 offset:35840
	s_waitcnt lgkmcnt(0)
	v_mfma_f32_16x16x32_bf16 v[44:47], v[80:83], v[84:87], v[44:47]
	ds_read_b128 v[80:83], v160 offset:64
	ds_read_b64_tr_b16 v[84:85], v200 offset:43008
	ds_read_b64_tr_b16 v[86:87], v201 offset:44032
	s_waitcnt lgkmcnt(0)
	v_mfma_f32_16x16x32_bf16 v[16:19], v[80:83], v[84:87], v[16:19]
	ds_read_b64_tr_b16 v[84:85], v202 offset:43008
	ds_read_b64_tr_b16 v[86:87], v203 offset:44032
	s_waitcnt lgkmcnt(0)
	v_mfma_f32_16x16x32_bf16 v[20:23], v[80:83], v[84:87], v[20:23]
	ds_read_b64_tr_b16 v[84:85], v204 offset:43008
	ds_read_b64_tr_b16 v[86:87], v205 offset:44032
	s_waitcnt lgkmcnt(0)
	v_mfma_f32_16x16x32_bf16 v[24:27], v[80:83], v[84:87], v[24:27]
	ds_read_b64_tr_b16 v[84:85], v206 offset:43008
	ds_read_b64_tr_b16 v[86:87], v207 offset:44032
	s_waitcnt lgkmcnt(0)
	v_mfma_f32_16x16x32_bf16 v[28:31], v[80:83], v[84:87], v[28:31]
	ds_read_b64_tr_b16 v[84:85], v208 offset:43008
	ds_read_b64_tr_b16 v[86:87], v209 offset:44032
	s_waitcnt lgkmcnt(0)
	v_mfma_f32_16x16x32_bf16 v[32:35], v[80:83], v[84:87], v[32:35]
	ds_read_b64_tr_b16 v[84:85], v210 offset:43008
	ds_read_b64_tr_b16 v[86:87], v211 offset:44032
	s_waitcnt lgkmcnt(0)
	v_mfma_f32_16x16x32_bf16 v[36:39], v[80:83], v[84:87], v[36:39]
	ds_read_b64_tr_b16 v[84:85], v212 offset:43008
	ds_read_b64_tr_b16 v[86:87], v213 offset:44032
	s_waitcnt lgkmcnt(0)
	v_mfma_f32_16x16x32_bf16 v[40:43], v[80:83], v[84:87], v[40:43]
	ds_read_b64_tr_b16 v[84:85], v214 offset:43008
	ds_read_b64_tr_b16 v[86:87], v215 offset:44032
	s_waitcnt lgkmcnt(0)
	v_mfma_f32_16x16x32_bf16 v[44:47], v[80:83], v[84:87], v[44:47]
	s_cbranch_scc1 .LBB0_335
	v_mov_b32_e32 v217, v128
	v_mov_b32_e32 v218, v145
	v_mov_b32_e32 v219, v144
	v_mov_b32_e32 v220, v221
	s_mov_b32 s3, s20
	s_branch .LBB0_348

; __device__ __forceinline__ bf16_t f2bf(float f) { return (bf16_t)((__float_as_uint(f) + 0x8000u) >> 16); }
; #define MFMA16(a, b, c) __builtin_amdgcn_mfma_f32_16x16x32_bf16(a, b, c, 0, 0, 0)
; __device__ __forceinline__ void hgrn_pass3(const Params& p, int l, bf16_t* PROJ, const bf16_t* STB, LAS unsigned char* L, int item) {
;     ...
;     for (int s2 = 0; s2 < 2; ++s2) { const int st = sh * 2 + s2; f32x4 a4 = {0.f, 0.f, 0.f, 0.f};
;         if (st <= tt) {
; #pragma unroll
;             for (int ks = 0; ks < 4; ++ks) a4 = MFMA16(LDFRAG(Qt, tt * 16 + fr, 136, ks * 32 + fq * 8), LDFRAG(Kt, st * 16 + fr, 136, ks * 32 + fq * 8), a4); }
; #pragma unroll
;         for (int jj = 0; jj < 4; ++jj) { const int t = tt * 16 + fq * 4 + jj, s = st * 16 + fr; At[t * 72 + s] = f2bf(s <= t ? a4[jj] : 0.f); } }
;     f32x4 O[4];
; #pragma unroll
;     for (int e = 0; e < 4; ++e) O[e] = (f32x4){0.f, 0.f, 0.f, 0.f};
; #pragma unroll
;     for (int ks = 0; ks < 4; ++ks) { const bf16x8 a = LDFRAG(Qd, tt * 16 + fr, 136, ks * 32 + fq * 8);
; #pragma unroll
;         for (int e = 0; e < 4; ++e) O[e] = MFMA16(a, sfr[ks][e], O[e]); }
;     __syncthreads();
; #pragma unroll
;     for (int ks = 0; ks < 2; ++ks) { const bf16x8 a = LDFRAG(At, tt * 16 + fr, 72, ks * 32 + fq * 8);
; #pragma unroll
;         for (int e = 0; e < 4; ++e) O[e] = MFMA16(a, v_frag(Vs, lane, sh * 4 + e, ks), O[e]); }
; #pragma unroll
;     for (int jj = 0; jj < 4; ++jj) { float ss = 0.f;
; #pragma unroll
;         for (int e = 0; e < 4; ++e) ss += O[e][jj] * O[e][jj];
;         ss += __shfl_xor(ss, 1); ss += __shfl_xor(ss, 2); ss += __shfl_xor(ss, 4); ss += __shfl_xor(ss, 8);
;         if (fr == 0) rowsq[sh * 64 + tt * 16 + fq * 4 + jj] = ss; }
.LBB0_463:
	s_or_b64 exec, exec, s[8:9]
	v_mul_u32_u24_e32 v71, 0x90, v68
	s_nop 5
	v_add_u32_e32 v64, 0x8000, v64
	v_cmp_le_i32_e32 vcc, v106, v68
	v_lshlrev_b32_e32 v105, 1, v106
	v_add3_u32 v71, s61, v71, v105
	v_cndmask_b32_sdwa v64, v178, v64, vcc dst_sel:DWORD dst_unused:UNUSED_PAD src0_sel:DWORD src1_sel:WORD_1
	ds_write_b16 v71, v64
	v_add_u32_e32 v64, 0x8000, v65
	v_lshrrev_b32_e32 v64, 16, v64
	v_cmp_le_i32_e32 vcc, v106, v72
	v_add3_u32 v65, s61, v103, v105
	v_add_u32_e32 v70, v70, v136
	v_cndmask_b32_e32 v64, 0, v64, vcc
	ds_write_b16 v65, v64
	v_add_u32_e32 v64, 0x8000, v66
	v_lshrrev_b32_e32 v64, 16, v64
	v_cmp_le_i32_e32 vcc, v106, v73
	v_add3_u32 v65, s61, v104, v105
	s_nop 0
	v_cndmask_b32_e32 v64, 0, v64, vcc
	ds_write_b16 v65, v64
	v_add_u32_e32 v64, 0x8000, v67
	v_lshrrev_b32_e32 v64, 16, v64
	v_cmp_le_i32_e32 vcc, v106, v74
	v_add3_u32 v65, s61, v75, v105
	s_nop 0
	v_cndmask_b32_e32 v64, 0, v64, vcc
	ds_write_b16 v65, v64
	ds_read_b128 v[64:67], v70 offset:37376
	s_waitcnt vmcnt(31) lgkmcnt(0)
	v_mfma_f32_16x16x32_bf16 v[24:27], v[64:67], v[24:27], 0
	s_waitcnt vmcnt(30)
	v_mfma_f32_16x16x32_bf16 v[32:35], v[64:67], v[32:35], 0
	s_waitcnt vmcnt(29)
	v_mfma_f32_16x16x32_bf16 v[56:59], v[64:67], v[56:59], 0
	s_waitcnt vmcnt(28)
	v_mfma_f32_16x16x32_bf16 v[60:63], v[64:67], v[60:63], 0
	ds_read_b128 v[64:67], v70 offset:37440
	s_waitcnt vmcnt(27) lgkmcnt(0)
	v_mfma_f32_16x16x32_bf16 v[24:27], v[64:67], v[28:31], v[24:27]
	s_waitcnt vmcnt(26)
	v_mfma_f32_16x16x32_bf16 v[28:31], v[64:67], v[36:39], v[32:35]
	s_waitcnt vmcnt(25)
	v_mfma_f32_16x16x32_bf16 v[32:35], v[64:67], v[40:43], v[56:59]
	ds_read_b128 v[40:43], v70 offset:37504
	s_waitcnt vmcnt(23) lgkmcnt(0)
	v_mfma_f32_16x16x32_bf16 v[24:27], v[40:43], v[44:47], v[24:27]
	ds_read_b128 v[44:47], v70 offset:37568
	s_waitcnt lgkmcnt(0)
	s_barrier
	v_mfma_f32_16x16x32_bf16 v[36:39], v[64:67], v[52:55], v[60:63]
	s_waitcnt vmcnt(22)
	v_mfma_f32_16x16x32_bf16 v[28:31], v[40:43], v[48:51], v[28:31]
	v_and_b32_e32 v48, 63, v78
	s_waitcnt vmcnt(21)
	v_mfma_f32_16x16x32_bf16 v[20:23], v[40:43], v[20:23], v[32:35]
	s_waitcnt vmcnt(20)
	v_mfma_f32_16x16x32_bf16 v[0:3], v[40:43], v[0:3], v[36:39]
	s_nop 0
	v_mul_u32_u24_e32 v32, 0x90, v69
	v_add3_u32 v32, s61, v32, v136
	v_bfe_u32 v33, v78, 2, 2
	s_waitcnt vmcnt(19)
	v_mfma_f32_16x16x32_bf16 v[16:19], v[44:47], v[16:19], v[24:27]
	s_nop 2
	v_lshrrev_b32_e32 v24, 1, v48
	s_waitcnt vmcnt(18)
	v_mfma_f32_16x16x32_bf16 v[12:15], v[44:47], v[12:15], v[28:31]
	v_and_or_b32 v24, v24, 24, v33
	v_lshlrev_b32_e32 v25, 3, v102
	v_bfe_u32 v26, v48, 1, 1
	v_and_b32_e32 v28, 12, v78
	s_waitcnt vmcnt(17)
	v_mfma_f32_16x16x32_bf16 v[8:11], v[44:47], v[8:11], v[20:23]
	v_or_b32_e32 v27, v26, v25
	s_nop 1
	v_lshrrev_b32_e32 v20, 3, v78
	v_and_or_b32 v29, v20, 2, v28
	v_lshlrev_b32_e32 v20, 3, v48
	s_waitcnt vmcnt(16)
	v_mfma_f32_16x16x32_bf16 v[0:3], v[44:47], v[4:7], v[0:3]
	v_lshlrev_b32_e32 v22, 1, v101
	ds_read_b128 v[4:7], v32
	v_and_b32_e32 v20, 8, v20
	v_lshlrev_b32_e32 v23, 8, v24
	v_and_or_b32 v24, v22, 2, v28
	v_bitop3_b32 v21, v26, v29, v25 bitop3:0x36
	v_add3_u32 v25, 0, v20, v23
	v_bitop3_b32 v22, v24, v27, 1 bitop3:0x36
	v_lshl_add_u32 v28, v21, 4, v25
	v_lshl_add_u32 v30, v22, 4, v25
	ds_read_b64_tr_b16 v[20:21], v28 offset:54784
	ds_read_b64_tr_b16 v[22:23], v30 offset:55808
	v_or_b32_e32 v24, 1, v24
	s_waitcnt lgkmcnt(0)
	v_mfma_f32_16x16x32_bf16 v[16:19], v[4:7], v[20:23], v[16:19]
	v_bitop3_b32 v20, v27, v29, 2 bitop3:0x36
	v_bitop3_b32 v22, v27, v24, 2 bitop3:0x36
	v_lshl_add_u32 v31, v20, 4, v25
	v_lshl_add_u32 v33, v22, 4, v25
	ds_read_b64_tr_b16 v[20:21], v31 offset:54784
	ds_read_b64_tr_b16 v[22:23], v33 offset:55808
	s_waitcnt lgkmcnt(0)
	v_mfma_f32_16x16x32_bf16 v[12:15], v[4:7], v[20:23], v[12:15]
	v_bitop3_b32 v20, v27, v29, 4 bitop3:0x36
	v_bitop3_b32 v22, v27, v24, 4 bitop3:0x36
	v_lshl_add_u32 v34, v20, 4, v25
	v_lshl_add_u32 v35, v22, 4, v25
	ds_read_b64_tr_b16 v[20:21], v34 offset:54784
	ds_read_b64_tr_b16 v[22:23], v35 offset:55808
	s_waitcnt lgkmcnt(0)
	v_mfma_f32_16x16x32_bf16 v[8:11], v[4:7], v[20:23], v[8:11]
	v_bitop3_b32 v20, v27, v29, 6 bitop3:0x36
	v_bitop3_b32 v22, v27, v24, 6 bitop3:0x36
	v_lshl_add_u32 v29, v20, 4, v25
	ds_read_b64_tr_b16 v[20:21], v29 offset:54784
	v_lshl_add_u32 v36, v22, 4, v25
	ds_read_b64_tr_b16 v[22:23], v36 offset:55808
	ds_read_b128 v[24:27], v32 offset:64
	s_waitcnt lgkmcnt(1)
	v_mfma_f32_16x16x32_bf16 v[20:23], v[4:7], v[20:23], v[0:3]
	s_nop 2
	ds_read_b64_tr_b16 v[0:1], v28 offset:62976
	ds_read_b64_tr_b16 v[2:3], v30 offset:64000
	ds_read_b64_tr_b16 v[4:5], v31 offset:62976
	ds_read_b64_tr_b16 v[6:7], v33 offset:64000
	s_waitcnt lgkmcnt(0)
	v_mfma_f32_16x16x32_bf16 v[4:7], v[24:27], v[4:7], v[12:15]
	s_nop 2
	ds_read_b64_tr_b16 v[12:13], v34 offset:62976
	ds_read_b64_tr_b16 v[14:15], v35 offset:64000
	s_waitcnt lgkmcnt(0)
	v_mfma_f32_16x16x32_bf16 v[8:11], v[24:27], v[12:15], v[8:11]
	ds_read_b64_tr_b16 v[12:13], v29 offset:62976
	ds_read_b64_tr_b16 v[14:15], v36 offset:64000
	v_mfma_f32_16x16x32_bf16 v[0:3], v[24:27], v[0:3], v[16:19]
	s_waitcnt lgkmcnt(0)
	v_mfma_f32_16x16x32_bf16 v[12:15], v[24:27], v[12:15], v[20:23]
	s_nop 0
	v_and_b32_e32 v17, 64, v168
	v_xor_b32_e32 v16, 1, v168
	v_add_u32_e32 v17, 64, v17
	v_mul_f32_e32 v18, v4, v4
	v_cmp_lt_i32_e32 vcc, v16, v17
	v_fmac_f32_e32 v18, v0, v0
	v_fmac_f32_e32 v18, v8, v8
	v_cndmask_b32_e32 v16, v168, v16, vcc
	v_lshlrev_b32_e32 v43, 2, v16
	v_fmac_f32_e32 v18, v12, v12
	v_xor_b32_e32 v16, 2, v168
	v_cmp_lt_i32_e32 vcc, v16, v17
	s_waitcnt lgkmcnt(0)
	s_nop 1
	v_add_f32_dpp v18, v18, v18 quad_perm:[1,0,3,2] row_mask:0xf bank_mask:0xf
	v_cndmask_b32_e32 v16, v168, v16, vcc
	v_lshlrev_b32_e32 v52, 2, v16
	v_xor_b32_e32 v16, 4, v168
	v_cmp_lt_i32_e32 vcc, v16, v17
	s_waitcnt lgkmcnt(0)
	s_nop 1
	v_add_f32_dpp v18, v18, v18 quad_perm:[2,3,0,1] row_mask:0xf bank_mask:0xf
	v_cndmask_b32_e32 v16, v168, v16, vcc
	v_lshlrev_b32_e32 v53, 2, v16
	v_xor_b32_e32 v16, 8, v168
	v_cmp_lt_i32_e32 vcc, v16, v17
	s_waitcnt lgkmcnt(0)
	s_nop 1
	v_add_f32_dpp v17, v18, v18 row_half_mirror row_mask:0xf bank_mask:0xf
	v_cndmask_b32_e32 v16, v168, v16, vcc
	v_lshlrev_b32_e32 v54, 2, v16
	s_nop 1
	v_mov_b32_dpp v18, v17 row_mirror row_mask:0xf bank_mask:0xf
	v_and_b32_e32 v16, 0xffffff00, v78
	v_lshlrev_b32_e32 v19, 6, v79
	v_add3_u32 v16, 0, v16, v19
	v_cmp_eq_u32_e32 vcc, 0, v80
	v_add_u32_e32 v16, v16, v136
	s_and_saveexec_b64 s[8:9], vcc
	s_cbranch_execz .LBB0_465
	s_waitcnt lgkmcnt(0)
	v_add_f32_e32 v17, v17, v18
	ds_write_b32 v16, v17 offset:2048
; __device__ __forceinline__ void hgrn_pass3(const Params& p, int l, bf16_t* PROJ, const bf16_t* STB, LAS unsigned char* L, int item) {
;     ...
;     for (int jj = 0; jj < 4; ++jj) { float ss = 0.f;
; #pragma unroll
;         for (int e = 0; e < 4; ++e) ss += O[e][jj] * O[e][jj];
;         ss += __shfl_xor(ss, 1); ss += __shfl_xor(ss, 2); ss += __shfl_xor(ss, 4); ss += __shfl_xor(ss, 8);
;         if (fr == 0) rowsq[sh * 64 + tt * 16 + fq * 4 + jj] = ss; }
.LBB0_465:
	s_or_b64 exec, exec, s[8:9]
	v_mul_f32_e32 v17, v5, v5
	v_fmac_f32_e32 v17, v1, v1
	v_fmac_f32_e32 v17, v9, v9
	v_fmac_f32_e32 v17, v13, v13
	s_waitcnt lgkmcnt(0)
	s_waitcnt lgkmcnt(0)
	s_nop 1
	v_add_f32_dpp v17, v17, v17 quad_perm:[1,0,3,2] row_mask:0xf bank_mask:0xf
	s_waitcnt lgkmcnt(0)
	s_nop 1
	v_add_f32_dpp v17, v17, v17 quad_perm:[2,3,0,1] row_mask:0xf bank_mask:0xf
	s_waitcnt lgkmcnt(0)
	s_nop 1
	v_add_f32_dpp v17, v17, v17 row_half_mirror row_mask:0xf bank_mask:0xf
	s_nop 1
	v_mov_b32_dpp v18, v17 row_mirror row_mask:0xf bank_mask:0xf
	s_and_saveexec_b64 s[8:9], vcc
	s_cbranch_execz .LBB0_467
	s_waitcnt lgkmcnt(0)
	v_add_f32_e32 v17, v17, v18
	ds_write_b32 v16, v17 offset:2052
.LBB0_467:
	s_or_b64 exec, exec, s[8:9]
	v_mul_f32_e32 v17, v6, v6
	v_fmac_f32_e32 v17, v2, v2
	v_fmac_f32_e32 v17, v10, v10
	v_fmac_f32_e32 v17, v14, v14
	s_waitcnt lgkmcnt(0)
	s_waitcnt lgkmcnt(0)
	s_nop 1
	v_add_f32_dpp v17, v17, v17 quad_perm:[1,0,3,2] row_mask:0xf bank_mask:0xf
	s_waitcnt lgkmcnt(0)
	s_nop 1
	v_add_f32_dpp v17, v17, v17 quad_perm:[2,3,0,1] row_mask:0xf bank_mask:0xf
	s_waitcnt lgkmcnt(0)
	s_nop 1
	v_add_f32_dpp v17, v17, v17 row_half_mirror row_mask:0xf bank_mask:0xf
	s_nop 1
	v_mov_b32_dpp v18, v17 row_mirror row_mask:0xf bank_mask:0xf
	s_and_saveexec_b64 s[8:9], vcc
	s_cbranch_execz .LBB0_469
	s_waitcnt lgkmcnt(0)
	v_add_f32_e32 v17, v17, v18
	ds_write_b32 v16, v17 offset:2056
.LBB0_469:
	s_or_b64 exec, exec, s[8:9]
	v_mul_f32_e32 v17, v7, v7
	v_fmac_f32_e32 v17, v3, v3
	v_fmac_f32_e32 v17, v11, v11
	v_fmac_f32_e32 v17, v15, v15
	s_waitcnt lgkmcnt(0)
	s_waitcnt lgkmcnt(0)
	s_nop 1
	v_add_f32_dpp v17, v17, v17 quad_perm:[1,0,3,2] row_mask:0xf bank_mask:0xf
	s_waitcnt lgkmcnt(0)
	s_nop 1
	v_add_f32_dpp v17, v17, v17 quad_perm:[2,3,0,1] row_mask:0xf bank_mask:0xf
	s_waitcnt lgkmcnt(0)
	s_nop 1
	v_add_f32_dpp v17, v17, v17 row_half_mirror row_mask:0xf bank_mask:0xf
	s_nop 1
	v_mov_b32_dpp v18, v17 row_mirror row_mask:0xf bank_mask:0xf
	s_and_saveexec_b64 s[8:9], vcc
	s_cbranch_execz .LBB0_456
	s_waitcnt lgkmcnt(0)
	v_add_f32_e32 v17, v17, v18
	ds_write_b32 v16, v17 offset:2060
	s_branch .LBB0_456

; __device__ __forceinline__ bf16_t f2bf(float f) { return (bf16_t)((__float_as_uint(f) + 0x8000u) >> 16); }
; #define MFMA16(a, b, c) __builtin_amdgcn_mfma_f32_16x16x32_bf16(a, b, c, 0, 0, 0)
; __device__ __forceinline__ void ret_pass3(bf16_t* PROJ, const bf16_t* STC, LAS unsigned char* L, int item, const float (&cs)[4], const float (&sn)[4]) {
;     ...
;     for (int s2 = 0; s2 < 2; ++s2) { const int st = sh * 2 + s2; f32x4 a4 = {0.f, 0.f, 0.f, 0.f};
;         if (st <= tt) {
; #pragma unroll
;             for (int ks = 0; ks < 2; ++ks) a4 = MFMA16(LDFRAG(Qr, tt * 16 + fr, 72, ks * 32 + fq * 8), LDFRAG(Kr, st * 16 + fr, 72, ks * 32 + fq * 8), a4); }
; #pragma unroll
;         for (int jj = 0; jj < 4; ++jj) { const int t = tt * 16 + fq * 4 + jj, s = st * 16 + fr; At[t * 72 + s] = f2bf(s <= t ? a4[jj] * exp2f(lg * (float)(t - s)) : 0.f); } }
;     f32x4 O[4];
; #pragma unroll
;     for (int e = 0; e < 4; ++e) O[e] = (f32x4){0.f, 0.f, 0.f, 0.f};
; #pragma unroll
;     for (int ks = 0; ks < 2; ++ks) { const bf16x8 a = LDFRAG(Qdc, tt * 16 + fr, 72, ks * 32 + fq * 8);
; #pragma unroll
;         for (int e = 0; e < 4; ++e) O[e] = MFMA16(a, sfr[ks][e], O[e]); }
;     __syncthreads();
; #pragma unroll
;     for (int ks = 0; ks < 2; ++ks) { const bf16x8 a = LDFRAG(At, tt * 16 + fr, 72, ks * 32 + fq * 8);
; #pragma unroll
;         for (int e = 0; e < 4; ++e) O[e] = MFMA16(a, v_frag(Vs, lane, sh * 4 + e, ks), O[e]); }
; #pragma unroll
;     for (int jj = 0; jj < 4; ++jj) { float ss = 0.f;
; #pragma unroll
;         for (int e = 0; e < 4; ++e) ss += O[e][jj] * O[e][jj];
;         ss += __shfl_xor(ss, 1); ss += __shfl_xor(ss, 2); ss += __shfl_xor(ss, 4); ss += __shfl_xor(ss, 8);
;         if (fr == 0) rowsq[sh * 64 + tt * 16 + fq * 4 + jj] = ss; }
.LBB0_527:
	s_or_b64 exec, exec, s[12:13]
	ds_write_b16 v38, v32 offset:28624
	v_add_u32_e32 v37, v37, v136
	ds_read_b128 v[32:35], v37 offset:18944
	v_and_b32_e32 v39, 63, v63
	v_cmp_eq_u32_e32 vcc, 0, v65
	s_waitcnt lgkmcnt(0)
	v_mfma_f32_16x16x32_bf16 v[16:19], v[32:35], v[16:19], 0
	v_mfma_f32_16x16x32_bf16 v[20:23], v[32:35], v[20:23], 0
	v_mfma_f32_16x16x32_bf16 v[24:27], v[32:35], v[24:27], 0
	v_mfma_f32_16x16x32_bf16 v[28:31], v[32:35], v[28:31], 0
	ds_read_b128 v[32:35], v37 offset:19008
	s_waitcnt lgkmcnt(0)
	s_barrier
	v_mfma_f32_16x16x32_bf16 v[0:3], v[32:35], v[0:3], v[16:19]
	s_nop 2
	v_bfe_u32 v16, v63, 2, 2
	v_lshrrev_b32_e32 v17, 1, v39
	v_lshrrev_b32_e32 v18, 3, v63
	v_mfma_f32_16x16x32_bf16 v[4:7], v[32:35], v[4:7], v[20:23]
	s_nop 2
	v_and_b32_e32 v21, 12, v63
	v_mfma_f32_16x16x32_bf16 v[8:11], v[32:35], v[8:11], v[24:27]
	v_and_or_b32 v20, v17, 24, v16
	v_lshlrev_b32_e32 v16, 3, v83
	v_bfe_u32 v17, v39, 1, 1
	v_and_or_b32 v25, v18, 2, v21
	v_lshlrev_b32_e32 v18, 3, v39
	v_or_b32_e32 v24, v17, v16
	v_and_b32_e32 v22, 8, v18
	v_bitop3_b32 v23, v17, v25, v16 bitop3:0x36
	v_lshlrev_b32_e32 v26, 1, v82
	ds_read_b128 v[16:19], v37 offset:28160
	v_lshlrev_b32_e32 v20, 8, v20
	v_and_or_b32 v21, v26, 2, v21
	v_add3_u32 v27, 0, v22, v20
	v_bitop3_b32 v22, v21, v24, 1 bitop3:0x36
	v_mfma_f32_16x16x32_bf16 v[12:15], v[32:35], v[12:15], v[28:31]
	v_or_b32_e32 v26, 1, v21
	s_nop 1
	v_lshl_add_u32 v28, v23, 4, v27
	v_lshl_add_u32 v29, v22, 4, v27
	ds_read_b64_tr_b16 v[20:21], v28 offset:37376
	ds_read_b64_tr_b16 v[22:23], v29 offset:38400
	s_waitcnt lgkmcnt(0)
	v_mfma_f32_16x16x32_bf16 v[0:3], v[16:19], v[20:23], v[0:3]
	v_bitop3_b32 v20, v24, v25, 2 bitop3:0x36
	v_bitop3_b32 v22, v24, v26, 2 bitop3:0x36
	v_lshl_add_u32 v30, v20, 4, v27
	v_lshl_add_u32 v31, v22, 4, v27
	ds_read_b64_tr_b16 v[20:21], v30 offset:37376
	ds_read_b64_tr_b16 v[22:23], v31 offset:38400
	s_waitcnt lgkmcnt(0)
	v_mfma_f32_16x16x32_bf16 v[4:7], v[16:19], v[20:23], v[4:7]
	v_bitop3_b32 v20, v24, v25, 4 bitop3:0x36
	v_bitop3_b32 v22, v24, v26, 4 bitop3:0x36
	v_lshl_add_u32 v32, v20, 4, v27
	v_lshl_add_u32 v33, v22, 4, v27
	ds_read_b64_tr_b16 v[20:21], v32 offset:37376
	ds_read_b64_tr_b16 v[22:23], v33 offset:38400
	s_waitcnt lgkmcnt(0)
	v_mfma_f32_16x16x32_bf16 v[8:11], v[16:19], v[20:23], v[8:11]
	v_bitop3_b32 v20, v24, v25, 6 bitop3:0x36
	v_bitop3_b32 v22, v24, v26, 6 bitop3:0x36
	v_lshl_add_u32 v24, v20, 4, v27
	v_lshl_add_u32 v25, v22, 4, v27
	ds_read_b64_tr_b16 v[20:21], v24 offset:37376
	ds_read_b64_tr_b16 v[22:23], v25 offset:38400
	s_waitcnt lgkmcnt(0)
	v_mfma_f32_16x16x32_bf16 v[12:15], v[16:19], v[20:23], v[12:15]
	ds_read_b128 v[16:19], v37 offset:28224
	ds_read_b64_tr_b16 v[20:21], v28 offset:45568
	ds_read_b64_tr_b16 v[22:23], v29 offset:46592
	s_waitcnt lgkmcnt(0)
	v_mfma_f32_16x16x32_bf16 v[0:3], v[16:19], v[20:23], v[0:3]
	ds_read_b64_tr_b16 v[20:21], v30 offset:45568
	ds_read_b64_tr_b16 v[22:23], v31 offset:46592
	s_waitcnt lgkmcnt(0)
	v_mfma_f32_16x16x32_bf16 v[4:7], v[16:19], v[20:23], v[4:7]
	ds_read_b64_tr_b16 v[20:21], v32 offset:45568
	ds_read_b64_tr_b16 v[22:23], v33 offset:46592
	s_waitcnt lgkmcnt(0)
	v_mfma_f32_16x16x32_bf16 v[8:11], v[16:19], v[20:23], v[8:11]
	ds_read_b64_tr_b16 v[20:21], v24 offset:45568
	ds_read_b64_tr_b16 v[22:23], v25 offset:46592
	s_waitcnt lgkmcnt(0)
	v_mfma_f32_16x16x32_bf16 v[12:15], v[16:19], v[20:23], v[12:15]
	v_and_b32_e32 v16, 0xffffff00, v63
	v_lshlrev_b32_e32 v17, 6, v64
	v_add3_u32 v16, 0, v16, v17
	v_mul_f32_e32 v17, v4, v4
	v_fmac_f32_e32 v17, v0, v0
	v_fmac_f32_e32 v17, v8, v8
	s_nop 1
	v_fmac_f32_e32 v17, v12, v12
	v_add_u32_e32 v16, v16, v136
	s_waitcnt lgkmcnt(0)
	s_nop 1
	v_add_f32_dpp v17, v17, v17 quad_perm:[1,0,3,2] row_mask:0xf bank_mask:0xf
	s_waitcnt lgkmcnt(0)
	s_nop 1
	v_add_f32_dpp v17, v17, v17 quad_perm:[2,3,0,1] row_mask:0xf bank_mask:0xf
	s_waitcnt lgkmcnt(0)
	s_nop 1
	v_add_f32_dpp v17, v17, v17 row_half_mirror row_mask:0xf bank_mask:0xf
	s_nop 1
	v_mov_b32_dpp v18, v17 row_mirror row_mask:0xf bank_mask:0xf
	s_and_saveexec_b64 s[12:13], vcc
	s_cbranch_execz .LBB0_529
	s_waitcnt lgkmcnt(0)
	v_add_f32_e32 v17, v17, v18
	ds_write_b32 v16, v17
.LBB0_529:
	s_or_b64 exec, exec, s[12:13]
	v_mul_f32_e32 v17, v5, v5
	v_fmac_f32_e32 v17, v1, v1
	v_fmac_f32_e32 v17, v9, v9
	v_fmac_f32_e32 v17, v13, v13
	s_waitcnt lgkmcnt(0)
	s_waitcnt lgkmcnt(0)
	s_nop 1
	v_add_f32_dpp v17, v17, v17 quad_perm:[1,0,3,2] row_mask:0xf bank_mask:0xf
	s_waitcnt lgkmcnt(0)
	s_nop 1
	v_add_f32_dpp v17, v17, v17 quad_perm:[2,3,0,1] row_mask:0xf bank_mask:0xf
	s_waitcnt lgkmcnt(0)
	s_nop 1
	v_add_f32_dpp v17, v17, v17 row_half_mirror row_mask:0xf bank_mask:0xf
	s_nop 1
	v_mov_b32_dpp v18, v17 row_mirror row_mask:0xf bank_mask:0xf
	s_and_saveexec_b64 s[12:13], vcc
	s_cbranch_execz .LBB0_531
	s_waitcnt lgkmcnt(0)
	v_add_f32_e32 v17, v17, v18
	ds_write_b32 v16, v17 offset:4
.LBB0_531:
	s_or_b64 exec, exec, s[12:13]
	v_mul_f32_e32 v17, v6, v6
	v_fmac_f32_e32 v17, v2, v2
	v_fmac_f32_e32 v17, v10, v10
	v_fmac_f32_e32 v17, v14, v14
	s_waitcnt lgkmcnt(0)
	s_waitcnt lgkmcnt(0)
	s_nop 1
	v_add_f32_dpp v17, v17, v17 quad_perm:[1,0,3,2] row_mask:0xf bank_mask:0xf
	s_waitcnt lgkmcnt(0)
	s_nop 1
	v_add_f32_dpp v17, v17, v17 quad_perm:[2,3,0,1] row_mask:0xf bank_mask:0xf
	s_waitcnt lgkmcnt(0)
	s_nop 1
	v_add_f32_dpp v17, v17, v17 row_half_mirror row_mask:0xf bank_mask:0xf
	s_nop 1
	v_mov_b32_dpp v18, v17 row_mirror row_mask:0xf bank_mask:0xf
	s_and_saveexec_b64 s[12:13], vcc
	s_cbranch_execz .LBB0_533
	s_waitcnt lgkmcnt(0)
	v_add_f32_e32 v17, v17, v18
	ds_write_b32 v16, v17 offset:8
.LBB0_533:
	s_or_b64 exec, exec, s[12:13]
	v_mul_f32_e32 v17, v7, v7
	v_fmac_f32_e32 v17, v3, v3
	v_fmac_f32_e32 v17, v11, v11
	v_fmac_f32_e32 v17, v15, v15
	s_waitcnt lgkmcnt(0)
	s_waitcnt lgkmcnt(0)
	s_nop 1
	v_add_f32_dpp v17, v17, v17 quad_perm:[1,0,3,2] row_mask:0xf bank_mask:0xf
	s_waitcnt lgkmcnt(0)
	s_nop 1
	v_add_f32_dpp v17, v17, v17 quad_perm:[2,3,0,1] row_mask:0xf bank_mask:0xf
	s_waitcnt lgkmcnt(0)
	s_nop 1
	v_add_f32_dpp v17, v17, v17 row_half_mirror row_mask:0xf bank_mask:0xf
	s_nop 1
	v_mov_b32_dpp v18, v17 row_mirror row_mask:0xf bank_mask:0xf
	s_and_saveexec_b64 s[12:13], vcc
	s_cbranch_execz .LBB0_506
	s_waitcnt lgkmcnt(0)
	v_add_f32_e32 v17, v17, v18
	ds_write_b32 v16, v17 offset:12
	s_branch .LBB0_506
